# v78: v68 without the s_sleep between polls in the all-poll loops of the XCD-local seams
# speedup vs baseline: 1.0024x; 1.0024x over previous
.Llb_lspin_g2:
	global_load_dword v6, v4, s[100:101] sc1
	v_add_u32_e32 v5, 1, v5
	s_waitcnt vmcnt(0)
	v_cmp_gt_u32_e32 vcc, s98, v6
	s_cmp_eq_u64 vcc, 0
	s_cbranch_scc1 .Llb_lrel_g2
	v_readfirstlane_b32 vcc_lo, v5
	s_cmp_lt_u32 vcc_lo, 0x2000
	s_cbranch_scc1 .Llb_lspin_g2
